# GLA chain step: q fragments read with ds_read_b64 pairs straight into the MFMA operand layout (48 v_mov per step dropped), b128 reads first, counted lgkmcnt waits
# baseline (speedup 1.0000x reference)
.LBB0_167:
	s_or_b64 exec, exec, s[40:41]
	v_add_u32_e32 v151, v113, v136
	v_add_u32_e32 v129, v111, v136
	s_cmp_gt_u32 s12, 3
	v_add_u32_e32 v152, v113, v137
	ds_read_b128 v[106:109], v151 offset:40960
	ds_read_b128 v[102:105], v152 offset:40960
	v_add_u32_e32 v0, v111, v137
	ds_read_b128 v[154:157], v129 offset:32768
	ds_read_b128 v[158:161], v129 offset:34816
	ds_read_b128 v[162:165], v0 offset:32768
	ds_read_b128 v[166:169], v0 offset:34816
	ds_read_b128 v[174:177], v129 offset:36864
	ds_read_b128 v[178:181], v129 offset:38912
	ds_read_b128 v[204:207], v0 offset:36864
	ds_read_b128 v[208:211], v0 offset:38912
	ds_read_b64 v[212:213], v143
	ds_read_b64 v[214:215], v144
	ds_read_b64 v[200:201], v143 offset:4096
	ds_read_b64 v[202:203], v144 offset:4096
	ds_read_b64 v[170:171], v143 offset:8192
	ds_read_b64 v[172:173], v144 offset:8192
	ds_read_b64 v[220:221], v143 offset:12288
	ds_read_b64 v[222:223], v144 offset:12288
	ds_read_b64 v[216:217], v145
	ds_read_b64 v[218:219], v146
	ds_read_b64 v[228:229], v145 offset:4096
	ds_read_b64 v[230:231], v146 offset:4096
	ds_read_b64 v[224:225], v145 offset:8192
	ds_read_b64 v[226:227], v146 offset:8192
	ds_read_b64 v[236:237], v145 offset:12288
	ds_read_b64 v[238:239], v146 offset:12288
	s_cselect_b32 s13, 39, 3
	s_add_i32 s13, s13, s10
	s_add_i32 s13, s13, 1
	s_and_b64 s[14:15], s[22:23], exec
	s_cselect_b32 s12, s12, s13
	s_waitcnt lgkmcnt(15)
	v_mfma_f32_16x16x32_bf16 v[154:157], v[106:109], v[154:157], 0
	v_mfma_f32_16x16x32_bf16 v[158:161], v[106:109], v[158:161], 0
	v_mfma_f32_16x16x32_bf16 v[154:157], v[102:105], v[162:165], v[154:157]
	v_mfma_f32_16x16x32_bf16 v[158:161], v[102:105], v[166:169], v[158:161]
	v_mfma_f32_16x16x32_bf16 v[162:165], v[106:109], v[174:177], 0
	v_mfma_f32_16x16x32_bf16 v[166:169], v[106:109], v[178:181], 0
	v_mfma_f32_16x16x32_bf16 v[162:165], v[102:105], v[204:207], v[162:165]
	v_mfma_f32_16x16x32_bf16 v[166:169], v[102:105], v[208:211], v[166:169]
	ds_read_b64 v[208:209], v147
	ds_read_b64 v[210:211], v148
	ds_read_b64 v[178:179], v147 offset:4096
	ds_read_b64 v[180:181], v148 offset:4096
	ds_read_b64 v[174:175], v147 offset:8192
	ds_read_b64 v[176:177], v148 offset:8192
	ds_read_b64 v[232:233], v147 offset:12288
	ds_read_b64 v[234:235], v148 offset:12288
	ds_read_b64 v[204:205], v149
	ds_read_b64 v[206:207], v150
	ds_read_b64 v[244:245], v149 offset:4096
	ds_read_b64 v[246:247], v150 offset:4096
	ds_read_b64 v[240:241], v149 offset:8192
	ds_read_b64 v[242:243], v150 offset:8192
	ds_read_b64 v[192:193], v149 offset:12288
	ds_read_b64 v[194:195], v150 offset:12288
	s_waitcnt lgkmcnt(15)
	v_mfma_f32_16x16x32_bf16 v[154:157], v[42:45], v[212:215], v[154:157]
	v_mfma_f32_16x16x32_bf16 v[158:161], v[42:45], v[200:203], v[158:161]
	v_mfma_f32_16x16x32_bf16 v[162:165], v[42:45], v[170:173], v[162:165]
	v_mfma_f32_16x16x32_bf16 v[42:45], v[42:45], v[220:223], v[166:169]
	v_mfma_f32_16x16x32_bf16 v[154:157], v[38:41], v[216:219], v[154:157]
	v_mfma_f32_16x16x32_bf16 v[158:161], v[38:41], v[228:231], v[158:161]
	v_mfma_f32_16x16x32_bf16 v[162:165], v[38:41], v[224:227], v[162:165]
	v_mfma_f32_16x16x32_bf16 v[38:41], v[38:41], v[236:239], v[42:45]
	s_nop 3
	ds_read_b128 v[42:45], v135 offset:49152
	ds_read_b128 v[166:169], v135 offset:49216
	ds_read_b128 v[170:173], v129 offset:16384
	ds_read_b128 v[200:203], v129 offset:18432
	ds_read_b128 v[212:215], v0 offset:16384
	ds_read_b128 v[216:219], v0 offset:18432
	s_waitcnt lgkmcnt(6)
	v_mfma_f32_16x16x32_bf16 v[154:157], v[22:25], v[208:211], v[154:157]
	v_mfma_f32_16x16x32_bf16 v[158:161], v[22:25], v[178:181], v[158:161]
	v_mfma_f32_16x16x32_bf16 v[162:165], v[22:25], v[174:177], v[162:165]
	v_mfma_f32_16x16x32_bf16 v[22:25], v[22:25], v[232:235], v[38:41]
	v_mfma_f32_16x16x32_bf16 v[38:41], v[18:21], v[204:207], v[154:157]
	v_mfma_f32_16x16x32_bf16 v[154:157], v[18:21], v[244:247], v[158:161]
	v_mfma_f32_16x16x32_bf16 v[158:161], v[18:21], v[240:243], v[162:165]
	v_mfma_f32_16x16x32_bf16 v[18:21], v[18:21], v[192:195], v[22:25]
	s_nop 3
	ds_read_b128 v[22:25], v135 offset:49280
	ds_read_b128 v[162:165], v135 offset:49344
	ds_read_b128 v[174:177], v129 offset:20480
	ds_read_b128 v[178:181], v129 offset:22528
	ds_read_b128 v[192:195], v0 offset:20480
	ds_read_b128 v[204:207], v0 offset:22528
	s_waitcnt lgkmcnt(0)
	v_pk_mul_f32 v[8:9], v[8:9], v[44:45]
	v_pk_mul_f32 v[6:7], v[6:7], v[42:43]
	v_pk_mul_f32 v[12:13], v[12:13], v[168:169]
	v_pk_mul_f32 v[10:11], v[10:11], v[166:167]
	v_mfma_f32_16x16x32_bf16 v[6:9], v[170:173], v[106:109], v[6:9]
	s_nop 0
	v_mfma_f32_16x16x32_bf16 v[10:13], v[200:203], v[106:109], v[10:13]
	v_mfma_f32_16x16x32_bf16 v[6:9], v[212:215], v[102:105], v[6:9]
	v_mfma_f32_16x16x32_bf16 v[10:13], v[216:219], v[102:105], v[10:13]
	s_lshl_b32 s12, s12, 6
	s_ashr_i32 s13, s12, 31
	v_lshl_add_u64 v[42:43], v[130:131], 0, s[12:13]
	v_cvt_pk_bf16_f32 v38, v38, v39
	v_cvt_pk_bf16_f32 v39, v40, v41
	v_lshlrev_b64 v[40:41], 11, v[42:43]
	v_lshl_add_u64 v[40:41], v[132:133], 0, v[40:41]
	v_add_co_u32_e32 v42, vcc, s3, v40
	global_store_dwordx2 v[40:41], v[38:39], off
	v_cvt_pk_bf16_f32 v38, v154, v155
	v_cvt_pk_bf16_f32 v39, v156, v157
	v_addc_co_u32_e32 v43, vcc, 0, v41, vcc
	global_store_dwordx2 v[42:43], v[38:39], off
	v_add_co_u32_e32 v42, vcc, s36, v40
	s_mov_b32 s12, 0x18000
	s_nop 0
	v_addc_co_u32_e32 v43, vcc, 0, v41, vcc
	v_cvt_pk_bf16_f32 v18, v18, v19
	v_cvt_pk_bf16_f32 v19, v20, v21
	v_add_co_u32_e32 v20, vcc, s12, v40
	v_cvt_pk_bf16_f32 v38, v158, v159
	v_cvt_pk_bf16_f32 v39, v160, v161
	v_addc_co_u32_e32 v21, vcc, 0, v41, vcc
	global_store_dwordx2 v[42:43], v[38:39], off
	global_store_dwordx2 v[20:21], v[18:19], off
	ds_read_b128 v[18:21], v135 offset:49408
	ds_read_b128 v[38:41], v135 offset:49472
	ds_read_b128 v[42:45], v129 offset:24576
	ds_read_b128 v[154:157], v129 offset:26624
	ds_read_b128 v[158:161], v0 offset:24576
	ds_read_b128 v[166:169], v0 offset:26624
	v_pk_mul_f32 v[16:17], v[16:17], v[24:25]
	v_pk_mul_f32 v[14:15], v[14:15], v[22:23]
	v_pk_mul_f32 v[24:25], v[28:29], v[164:165]
	v_pk_mul_f32 v[22:23], v[26:27], v[162:163]
	v_mfma_f32_16x16x32_bf16 v[14:17], v[174:177], v[106:109], v[14:17]
	s_nop 0
	v_mfma_f32_16x16x32_bf16 v[22:25], v[178:181], v[106:109], v[22:25]
	v_mfma_f32_16x16x32_bf16 v[14:17], v[192:195], v[102:105], v[14:17]
	v_mfma_f32_16x16x32_bf16 v[26:29], v[204:207], v[102:105], v[22:25]
	s_nop 5
	ds_read_b128 v[22:25], v135 offset:49536
	ds_read_b128 v[162:165], v135 offset:49600
	ds_read_b128 v[170:173], v129 offset:28672
	ds_read_b128 v[174:177], v129 offset:30720
	ds_read_b128 v[178:181], v0 offset:28672
	ds_read_b128 v[192:195], v0 offset:30720
	s_waitcnt lgkmcnt(0)
	v_pk_mul_f32 v[20:21], v[32:33], v[20:21]
	v_pk_mul_f32 v[18:19], v[30:31], v[18:19]
	s_nop 1
	v_mfma_f32_16x16x32_bf16 v[18:21], v[42:45], v[106:109], v[18:21]
	v_mfma_f32_16x16x32_bf16 v[30:33], v[158:161], v[102:105], v[18:21]
	s_nop 6
	v_mul_f32_e64 v20, v36, v40
	v_mul_f32_e64 v21, v37, v41
	v_pk_mul_f32 v[18:19], v[34:35], v[38:39]
	s_nop 1
	v_mfma_f32_16x16x32_bf16 v[18:21], v[154:157], v[106:109], v[18:21]
	v_mfma_f32_16x16x32_bf16 v[34:37], v[166:169], v[102:105], v[18:21]
	s_nop 6
	v_mul_f32_e64 v20, v52, v24
	v_mul_f32_e64 v21, v53, v25
	v_pk_mul_f32 v[18:19], v[50:51], v[22:23]
	v_pk_mul_f32 v[24:25], v[48:49], v[164:165]
	v_pk_mul_f32 v[22:23], v[46:47], v[162:163]
	v_mfma_f32_16x16x32_bf16 v[18:21], v[170:173], v[106:109], v[18:21]
	s_barrier
	v_mfma_f32_16x16x32_bf16 v[50:53], v[178:181], v[102:105], v[18:21]
	s_waitcnt vmcnt(0)
	ds_write_b128 v138, v[54:57]
	ds_write_b128 v139, v[58:61]
	ds_write_b128 v140, v[62:65]
	ds_write_b128 v141, v[66:69]
	ds_write_b128 v142, v[70:73] offset:16384
	ds_write_b128 v142, v[74:77] offset:20480
	ds_write_b128 v142, v[78:81] offset:24576
	ds_write_b128 v142, v[82:85] offset:28672
	ds_write_b128 v142, v[86:89] offset:32768
	ds_write_b128 v142, v[90:93] offset:36864
	ds_write_b128 v142, v[94:97] offset:40960
	ds_write_b128 v142, v[98:101] offset:45056
	v_mfma_f32_16x16x32_bf16 v[18:21], v[174:177], v[106:109], v[22:25]
	v_mfma_f32_16x16x32_bf16 v[46:49], v[192:195], v[102:105], v[18:21]
	s_and_saveexec_b64 s[28:29], s[38:39]
	ds_write_b128 v112, v[2:5] offset:49152
	s_or_b64 exec, exec, s[28:29]
	s_add_i32 s10, s10, -1
	v_cvt_pk_bf16_f32 v42, v6, v7
	v_cvt_pk_bf16_f32 v43, v8, v9
	v_cvt_pk_bf16_f32 v44, v10, v11
	v_cvt_pk_bf16_f32 v45, v12, v13
	v_cvt_pk_bf16_f32 v38, v14, v15
	v_cvt_pk_bf16_f32 v39, v16, v17
	v_cvt_pk_bf16_f32 v40, v26, v27
	v_cvt_pk_bf16_f32 v41, v28, v29
	v_cvt_pk_bf16_f32 v22, v30, v31
	v_cvt_pk_bf16_f32 v23, v32, v33
	v_cvt_pk_bf16_f32 v24, v34, v35
	v_cvt_pk_bf16_f32 v25, v36, v37
	v_cvt_pk_bf16_f32 v18, v50, v51
	v_cvt_pk_bf16_f32 v19, v52, v53
	v_cvt_pk_bf16_f32 v20, v46, v47
	v_cvt_pk_bf16_f32 v21, v48, v49
	s_cmp_eq_u32 s11, 35
	s_waitcnt lgkmcnt(0)
	s_barrier
	s_cbranch_scc1 .LBB0_159
	s_mov_b32 s12, s11
	s_branch .LBB0_165
